# G1 and G3: the wait for the next unit's prefetched operands moved from the end of the gate columns to their first consumer after the matrix section
# speedup vs baseline: 1.0027x; 1.0027x over previous
; __device__ __forceinline__ float silu_fast(float x) { return x * __builtin_amdgcn_rcpf(1.f + __expf(-x)); }
; __device__ __forceinline__ unsigned cvtpk(float lo, float hi) { unsigned r; asm volatile("v_cvt_pk_bf16_f32 %0, %1, %2" : "=v"(r) : "v"(lo), "v"(hi)); return r; }
; #define GLA_BAR() do { asm volatile("s_waitcnt lgkmcnt(0)" ::: "memory"); __builtin_amdgcn_s_barrier(); asm volatile("" ::: "memory"); } while (0)
; __device__ __forceinline__ void gla_g3_phase(LAS unsigned char* lds, const bf16_t* PROJ, const bf16_t* ALOW, const float* wa2, const float* ba, const float* gn, const bf16_t* UPD, bf16_t* MIXIN, int G, int tid) {
;     ...
;         GLA_BAR();
;         const float tot = (RED[32 * cb + i] + RED[64 + 32 * cb + i]) + (RED[128 + 32 * cb + i] + RED[192 + 32 * cb + i]);
;         const float rstd = rsqrtf(tot * (1.f / 128.f) + LN_EPS);
; #pragma unroll
;         for (int rg = 0; rg < 4; ++rg) { const int e = 32 * eb + 8 * rg + 4 * kg;
;             const f32x4 g4 = *(const f32x4*)(gn + e); const u32x2_t rr = cur.rr[rg];
;             const float r0 = __uint_as_float(rr.x << 16), r1 = __uint_as_float(rr.x & 0xffff0000u), r2 = __uint_as_float(rr.y << 16), r3 = __uint_as_float(rr.y & 0xffff0000u);
;             u32x2_t w; w.x = cvtpk(o[4 * rg] * rstd * g4[0] * pg8::silu_fast(r0), o[4 * rg + 1] * rstd * g4[1] * pg8::silu_fast(r1));
;             w.y = cvtpk(o[4 * rg + 2] * rstd * g4[2] * pg8::silu_fast(r2), o[4 * rg + 3] * rstd * g4[3] * pg8::silu_fast(r3));
;             *(u32x2_t*)(MIXIN + row * D + 512 + h * 128 + e) = w; }
;         GLA_BAR();
.LBB0_344:
	s_or_b64 exec, exec, s[6:7]
	s_waitcnt lgkmcnt(0)
	s_barrier
	ds_read2st64_b32 v[18:19], v130 offset0:144 offset1:145
	ds_read2st64_b32 v[20:21], v130 offset0:146 offset1:147
	v_and_b32_e32 v26, 0xffff0000, v124
	v_lshlrev_b32_e32 v28, 16, v125
	v_and_b32_e32 v30, 0xffff0000, v125
	s_waitcnt lgkmcnt(1)
	v_mov_b32_e32 v22, v18
	s_waitcnt lgkmcnt(0)
	v_mov_b32_e32 v23, v20
	v_mov_b32_e32 v20, v19
	v_pk_add_f32 v[18:19], v[22:23], v[20:21]
	v_mov_b64_e32 v[22:23], v[180:181]
	v_mov_b64_e32 v[24:25], v[182:183]
	v_add_f32_e32 v18, v18, v19
	v_fmamk_f32 v18, v18, 0x3c000000, v173
	v_cmp_gt_f32_e32 vcc, s81, v18
	v_mul_f32_e32 v19, 0x4b800000, v18
	s_and_b32 s4, s64, 0xffffe000
	v_cndmask_b32_e32 v18, v18, v19, vcc
	v_rsq_f32_e32 v18, v18
	s_and_b32 s5, s65, 0x1fc0
	s_or_b32 s4, s4, s5
	v_or_b32_e32 v16, s4, v128
	v_mul_f32_e32 v19, 0x45800000, v18
	v_cndmask_b32_e32 v20, v18, v19, vcc
	v_lshlrev_b32_e32 v18, 16, v124
	v_mul_f32_e32 v19, v0, v20
	v_mul_f32_e32 v0, 0xbfb8aa3b, v18
	v_exp_f32_e32 v0, v0
	v_mul_f32_e32 v27, v1, v20
	v_mul_f32_e32 v29, v2, v20
	v_ashrrev_i32_e32 v17, 31, v16
	v_add_f32_e32 v0, 1.0, v0
	v_rcp_f32_e32 v72, v0
	v_mul_f32_e32 v0, 0xbfb8aa3b, v26
	v_exp_f32_e32 v0, v0
	v_readlane_b32 s4, v250, 10
	v_lshlrev_b64 v[16:17], 11, v[16:17]
	v_readlane_b32 s5, v250, 11
	v_add_f32_e32 v0, 1.0, v0
	v_mul_f32_e32 v31, v3, v20
	v_lshl_add_u64 v[16:17], s[4:5], 0, v[16:17]
	s_lshl_b32 s74, s74, 8
	v_lshl_add_u64 v[16:17], v[16:17], 0, s[74:75]
	v_mul_f32_e32 v3, v4, v20
	v_readlane_b32 s4, v253, 0
	s_add_i32 s65, s65, s4
	v_readlane_b32 s4, v253, 42
	s_add_i32 s64, s64, s4
	v_readlane_b32 s4, v253, 18
	v_readlane_b32 s5, v253, 19
	s_waitcnt vmcnt(0)
	v_mov_b64_e32 v[78:79], v[62:63]
	v_mov_b64_e32 v[82:83], v[58:59]
	v_mov_b64_e32 v[86:87], v[54:55]
	v_lshl_add_u64 v[108:109], v[108:109], 0, s[4:5]
	s_and_b64 vcc, exec, s[92:93]
	v_mov_b64_e32 v[76:77], v[60:61]
	v_mov_b64_e32 v[80:81], v[56:57]
	v_mov_b64_e32 v[84:85], v[52:53]
	v_mov_b64_e32 v[124:125], v[118:119]
	s_mov_b32 s6, s70
	v_mov_b32_e32 v73, v22
	v_rcp_f32_e32 v22, v0
	v_pk_mul_f32 v[18:19], v[72:73], v[18:19]
	v_mov_b64_e32 v[74:75], v[50:51]
	v_mul_f32_e32 v18, v18, v19
	v_pk_mul_f32 v[0:1], v[22:23], v[26:27]
	v_and_b32_e32 v22, 0xffff0000, v122
	v_mul_f32_e32 v0, v0, v1
	v_cvt_pk_bf16_f32 v18, v18, v0
	v_mul_f32_e32 v0, 0xbfb8aa3b, v28
	v_exp_f32_e32 v0, v0
	v_mov_b32_e32 v1, v24
	v_mul_f32_e32 v23, v5, v20
	v_and_b32_e32 v26, 0xffff0000, v123
	v_add_f32_e32 v0, 1.0, v0
	v_rcp_f32_e32 v0, v0
	v_mul_f32_e32 v27, v7, v20
	v_mov_b64_e32 v[72:73], v[48:49]
	v_pk_mul_f32 v[0:1], v[0:1], v[28:29]
	s_nop 0
	v_mul_f32_e32 v2, v0, v1
	v_mul_f32_e32 v0, 0xbfb8aa3b, v30
	v_exp_f32_e32 v0, v0
	s_nop 0
	v_add_f32_e32 v0, 1.0, v0
	v_rcp_f32_e32 v24, v0
	s_nop 0
	v_pk_mul_f32 v[0:1], v[24:25], v[30:31]
	s_nop 0
	v_mul_f32_e32 v0, v0, v1
	v_cvt_pk_bf16_f32 v19, v2, v0
	v_lshl_add_u64 v[0:1], v[104:105], 1, v[16:17]
	global_store_dwordx2 v[0:1], v[18:19], off offset:1024
	v_mov_b64_e32 v[16:17], v[184:185]
	v_mov_b64_e32 v[18:19], v[186:187]
	v_lshlrev_b32_e32 v2, 16, v122
	v_mul_f32_e32 v4, 0xbfb8aa3b, v2
	v_exp_f32_e32 v4, v4
	v_lshlrev_b32_e32 v24, 16, v123
	v_mul_f32_e32 v25, v6, v20
	v_lshlrev_b32_e32 v6, 16, v120
	v_add_f32_e32 v4, 1.0, v4
	v_rcp_f32_e32 v28, v4
	v_mul_f32_e32 v7, 0xbfb8aa3b, v6
	v_exp_f32_e32 v7, v7
	v_mov_b64_e32 v[122:123], v[116:117]
	v_add_f32_e32 v7, 1.0, v7
	v_mov_b32_e32 v29, v16
	v_pk_mul_f32 v[2:3], v[28:29], v[2:3]
	v_mov_b32_e32 v5, v18
	v_mul_f32_e32 v4, v2, v3
	v_mul_f32_e32 v2, 0xbfb8aa3b, v22
	v_exp_f32_e32 v2, v2
	s_nop 0
	v_add_f32_e32 v2, 1.0, v2
	v_rcp_f32_e32 v16, v2
	s_nop 0
	v_pk_mul_f32 v[2:3], v[16:17], v[22:23]
	s_nop 0
	v_mul_f32_e32 v2, v2, v3
	v_mul_f32_e32 v3, 0xbfb8aa3b, v24
	v_exp_f32_e32 v3, v3
	v_cvt_pk_bf16_f32 v2, v4, v2
	v_and_b32_e32 v16, 0xffff0000, v120
	v_and_b32_e32 v22, 0xffff0000, v121
	v_add_f32_e32 v3, 1.0, v3
	v_rcp_f32_e32 v4, v3
	s_nop 0
	v_pk_mul_f32 v[4:5], v[4:5], v[24:25]
	s_nop 0
	v_mul_f32_e32 v3, v4, v5
	v_mul_f32_e32 v4, 0xbfb8aa3b, v26
	v_exp_f32_e32 v4, v4
	v_rcp_f32_e32 v24, v7
	v_mul_f32_e32 v25, v8, v20
	v_add_f32_e32 v4, 1.0, v4
	v_rcp_f32_e32 v18, v4
	s_nop 0
	v_pk_mul_f32 v[4:5], v[18:19], v[26:27]
	s_nop 0
	v_mul_f32_e32 v4, v4, v5
	v_cvt_pk_bf16_f32 v3, v3, v4
	global_store_dwordx2 v[0:1], v[2:3], off offset:1040
	v_mov_b64_e32 v[2:3], v[188:189]
	v_mov_b64_e32 v[4:5], v[190:191]
	v_lshlrev_b32_e32 v18, 16, v121
	v_mov_b64_e32 v[120:121], v[114:115]
	v_mov_b32_e32 v7, v2
	v_mul_f32_e32 v2, 0xbfb8aa3b, v16
	v_exp_f32_e32 v2, v2
	v_pk_mul_f32 v[6:7], v[24:25], v[6:7]
	v_mov_b32_e32 v17, v3
	v_mul_f32_e32 v8, v6, v7
	v_add_f32_e32 v2, 1.0, v2
	v_rcp_f32_e32 v6, v2
	v_mul_f32_e32 v7, v9, v20
	v_mov_b32_e32 v19, v4
	v_mul_f32_e32 v4, 0xbfb8aa3b, v22
	v_pk_mul_f32 v[2:3], v[6:7], v[16:17]
	v_exp_f32_e32 v4, v4
	v_mul_f32_e32 v2, v2, v3
	v_mul_f32_e32 v3, 0xbfb8aa3b, v18
	v_exp_f32_e32 v3, v3
	v_mul_f32_e32 v7, v10, v20
	v_add_f32_e32 v4, 1.0, v4
	v_mov_b32_e32 v23, v5
	v_add_f32_e32 v3, 1.0, v3
	v_rcp_f32_e32 v6, v3
	v_cvt_pk_bf16_f32 v2, v8, v2
	v_and_b32_e32 v8, 0xffff0000, v110
	v_lshlrev_b32_e32 v10, 16, v111
	v_pk_mul_f32 v[6:7], v[6:7], v[18:19]
	v_mul_f32_e32 v19, v12, v20
	v_mul_f32_e32 v3, v6, v7
	v_rcp_f32_e32 v6, v4
	v_mul_f32_e32 v7, v11, v20
	v_and_b32_e32 v16, 0xffff0000, v111
	v_pk_mul_f32 v[4:5], v[6:7], v[22:23]
	s_nop 0
	v_mul_f32_e32 v4, v4, v5
	v_cvt_pk_bf16_f32 v3, v3, v4
	global_store_dwordx2 v[0:1], v[2:3], off offset:1056
	v_mov_b64_e32 v[2:3], v[192:193]
	v_mov_b64_e32 v[4:5], v[194:195]
	v_lshlrev_b32_e32 v6, 16, v110
	v_mul_f32_e32 v7, 0xbfb8aa3b, v6
	v_exp_f32_e32 v7, v7
	v_mov_b64_e32 v[110:111], v[112:113]
	v_add_f32_e32 v7, 1.0, v7
	v_rcp_f32_e32 v18, v7
	v_mov_b32_e32 v7, v2
	v_mul_f32_e32 v2, 0xbfb8aa3b, v8
	v_exp_f32_e32 v2, v2
	v_pk_mul_f32 v[6:7], v[18:19], v[6:7]
	v_mov_b32_e32 v9, v3
	v_mul_f32_e32 v11, v6, v7
	v_add_f32_e32 v2, 1.0, v2
	v_rcp_f32_e32 v6, v2
	v_mul_f32_e32 v7, v13, v20
	v_mov_b32_e32 v17, v5
	v_pk_mul_f32 v[2:3], v[6:7], v[8:9]
	s_nop 0
	v_mul_f32_e32 v2, v2, v3
	v_mul_f32_e32 v3, 0xbfb8aa3b, v10
	v_exp_f32_e32 v3, v3
	v_cvt_pk_bf16_f32 v2, v11, v2
	v_mov_b32_e32 v11, v4
	v_mul_f32_e32 v4, 0xbfb8aa3b, v16
	v_add_f32_e32 v3, 1.0, v3
	v_rcp_f32_e32 v6, v3
	v_exp_f32_e32 v4, v4
	v_mul_f32_e32 v7, v14, v20
	v_pk_mul_f32 v[6:7], v[6:7], v[10:11]
	v_add_f32_e32 v4, 1.0, v4
	v_mul_f32_e32 v3, v6, v7
	v_rcp_f32_e32 v6, v4
	v_mul_f32_e32 v7, v15, v20
	v_mov_b64_e32 v[20:21], v[32:33]
	v_mov_b64_e32 v[12:13], v[68:69]
	v_pk_mul_f32 v[4:5], v[6:7], v[16:17]
	v_mov_b64_e32 v[16:17], v[36:37]
	v_mul_f32_e32 v4, v4, v5
	v_cvt_pk_bf16_f32 v3, v3, v4
	global_store_dwordx2 v[0:1], v[2:3], off offset:1072
	s_waitcnt lgkmcnt(0)
	s_barrier
; #define GLA_BAR() do { asm volatile("s_waitcnt lgkmcnt(0)" ::: "memory"); __builtin_amdgcn_s_barrier(); asm volatile("" ::: "memory"); } while (0)
; __device__ __forceinline__ void gla_g3_phase(LAS unsigned char* lds, const bf16_t* PROJ, const bf16_t* ALOW, const float* wa2, const float* ba, const float* gn, const bf16_t* UPD, bf16_t* MIXIN, int G, int tid) {
;     ...
;         GLA_BAR();
;         cur = nxt;
;     }
	v_mov_b64_e32 v[4:5], v[44:45]
	v_mov_b64_e32 v[0:1], v[40:41]
	v_mov_b64_e32 v[8:9], v[64:65]
	v_mov_b64_e32 v[18:19], v[38:39]
	v_mov_b64_e32 v[22:23], v[34:35]
	v_mov_b64_e32 v[6:7], v[46:47]
	v_mov_b64_e32 v[2:3], v[42:43]
	v_mov_b64_e32 v[14:15], v[70:71]
	v_mov_b64_e32 v[10:11], v[66:67]
	s_cbranch_vccnz .LBB0_418

; __device__ __forceinline__ void gla_bcum(const u32x4 a0, const u32x4 a1, const float* wa2, const float* ba, int h, int lane, int wave, float (&bc)[8], float (&bl)[8]) {
;     ...
;     for (int x = 0; x < 8; ++x) { const int col = h * 64 + 8 * wave + x; float z = ba[col];
; #pragma unroll
;         for (int i = 0; i < 16; ++i) z += al[i] * wa2[i * 256 + col];
;         float la = (fminf(z, 0.f) - __logf(1.f + __expf(-fabsf(z)))) * (1.f / 16.f);
;         la += __builtin_bit_cast(float, __builtin_amdgcn_update_dpp(0, __builtin_bit_cast(int, la), 0x111, 0xf, 0xf, true));
;         la += __builtin_bit_cast(float, __builtin_amdgcn_update_dpp(0, __builtin_bit_cast(int, la), 0x112, 0xf, 0xf, true));
;         la += __builtin_bit_cast(float, __builtin_amdgcn_update_dpp(0, __builtin_bit_cast(int, la), 0x114, 0xf, 0xf, true));
;         la += __builtin_bit_cast(float, __builtin_amdgcn_update_dpp(0, __builtin_bit_cast(int, la), 0x118, 0xf, 0xf, true));
;         const float t0 = __builtin_bit_cast(float, __builtin_amdgcn_readlane(__builtin_bit_cast(int, la), 15)), t1 = __builtin_bit_cast(float, __builtin_amdgcn_readlane(__builtin_bit_cast(int, la), 31)),
;                     t2 = __builtin_bit_cast(float, __builtin_amdgcn_readlane(__builtin_bit_cast(int, la), 47)), t3 = __builtin_bit_cast(float, __builtin_amdgcn_readlane(__builtin_bit_cast(int, la), 63));
;         la += (lane >= 48) ? (t0 + t1) + t2 : (lane >= 32) ? t0 + t1 : (lane >= 16) ? t0 : 0.f;
;         bc[x] = la; bl[x] = ((t0 + t1) + t2) + t3; }
.LBB0_401:
	s_andn2_saveexec_b64 vcc, vcc
	v_mov_b32_e32 v101, s71
	v_add_f32_e32 v101, s58, v101
	v_add_f32_e32 v101, s59, v101
	s_or_b64 exec, exec, vcc
	s_mov_b32 s4, 0xbfb8aa3b
	s_waitcnt lgkmcnt(0)
	v_mov_b32_e32 v102, s82
	v_fmac_f32_e32 v102, s83, v92
	v_fmac_f32_e32 v102, s84, v91
	v_fmac_f32_e32 v102, s85, v90
	v_fmac_f32_e32 v102, s86, v89
	v_fmac_f32_e32 v102, s87, v88
	v_fmac_f32_e32 v102, s88, v31
	v_fmac_f32_e32 v102, s89, v30
	v_fmac_f32_e32 v102, s90, v29
	v_fmac_f32_e32 v102, s91, v28
	v_fmac_f32_e32 v102, s94, v27
	v_fmac_f32_e32 v102, s95, v26
	v_fmac_f32_e32 v102, s96, v25
	v_fmac_f32_e32 v102, s97, v24
	v_fmac_f32_e32 v102, s51, v20
	v_fmac_f32_e32 v102, s52, v19
	v_fmac_f32_e32 v102, s53, v18
	v_readlane_b32 s82, v255, 29
	v_readlane_b32 s83, v255, 30
	v_readlane_b32 s84, v255, 31
	v_readlane_b32 s85, v255, 32
	v_readlane_b32 s86, v255, 33
	v_readlane_b32 s87, v255, 34
	v_readlane_b32 s88, v255, 35
	v_readlane_b32 s89, v255, 36
	v_readlane_b32 s90, v255, 37
	v_readlane_b32 s91, v255, 38
	v_readlane_b32 s94, v255, 39
	v_readlane_b32 s95, v255, 40
	v_readlane_b32 s96, v255, 41
	v_readlane_b32 s97, v255, 42
	v_readlane_b32 s51, v255, 43
	v_readlane_b32 s52, v255, 44
	v_readlane_b32 s53, v255, 45
	v_mul_f32_e64 v19, |v102|, s4
	v_exp_f32_e32 v19, v19
	s_mov_b32 s4, 0x3f317217
	v_min_f32_e32 v18, 0, v102
	v_add_f32_e32 v19, 1.0, v19
	v_cmp_gt_f32_e32 vcc, s81, v19
	s_nop 1
	v_cndmask_b32_e64 v20, 0, 32, vcc
	v_ldexp_f32 v19, v19, v20
	v_log_f32_e32 v19, v19
	s_nop 0
	v_mul_f32_e32 v20, 0x3f317217, v19
	v_fma_f32 v20, v19, s4, -v20
	v_fmac_f32_e32 v20, 0x3377d1cf, v19
	s_mov_b32 s4, 0x7f800000
	v_fmac_f32_e32 v20, 0x3f317217, v19
	v_cmp_lt_f32_e64 s[48:49], |v19|, s4
	s_nop 1
	v_cndmask_b32_e64 v19, v19, v20, s[48:49]
	v_cndmask_b32_e32 v20, 0, v231, vcc
	v_sub_f32_e32 v19, v19, v20
	v_sub_f32_e32 v18, v18, v19
	v_mul_f32_e32 v19, 0x3d800000, v18
	s_nop 1
	v_mov_b32_dpp v19, v19 row_shr:1 row_mask:0xf bank_mask:0xf bound_ctrl:1
	v_fmac_f32_e32 v19, 0x3d800000, v18
	s_nop 1
	v_add_f32_dpp v18, v19, v19 row_shr:2 row_mask:0xf bank_mask:0xf bound_ctrl:1
	s_nop 1
	v_add_f32_dpp v18, v18, v18 row_shr:4 row_mask:0xf bank_mask:0xf bound_ctrl:1
	s_nop 1
	v_add_f32_dpp v18, v18, v18 row_shr:8 row_mask:0xf bank_mask:0xf bound_ctrl:1
	s_nop 0
	v_readlane_b32 s58, v18, 15
	v_readlane_b32 s71, v18, 31
	v_readlane_b32 s59, v18, 47
	s_and_saveexec_b64 s[4:5], s[8:9]
	s_xor_b64 s[48:49], exec, s[4:5]
	s_cbranch_execz .LBB0_409
	s_and_saveexec_b64 s[4:5], s[10:11]
	s_xor_b64 s[6:7], exec, s[4:5]
	v_mov_b32_e32 v19, s58
	v_cndmask_b32_e64 v19, 0, v19, s[12:13]
	s_andn2_saveexec_b64 s[6:7], s[6:7]
	v_mov_b32_e32 v19, s71
	v_add_f32_e32 v19, s58, v19
	s_or_b64 exec, exec, s[6:7]

; #define LAS __attribute__((address_space(3)))
; #define GLA_BAR() do { asm volatile("s_waitcnt lgkmcnt(0)" ::: "memory"); __builtin_amdgcn_s_barrier(); asm volatile("" ::: "memory"); } while (0)
; __device__ __forceinline__ void gla_g1_phase(LAS unsigned char* lds, const bf16_t* PROJ, const bf16_t* ALOW, const float* wa2, const float* ba, float* UPD, float* DEC, int G, int tid) {
;     ...
;         for (int pc = 0; pc < 2; ++pc) { const int e0 = 64 * pc + 8 * wave; const u32x4 v = pc ? cur.v1 : cur.v0;
; #pragma unroll
;             for (int x = 0; x < 4; ++x) { VT[(e0 + 2 * x) * GP + lane] = (bf16_t)(v[x] & 0xffffu); VT[(e0 + 2 * x + 1) * GP + lane] = (bf16_t)(v[x] >> 16); } }
;         GLA_BAR();
;         const int eb = wave >> 1, dbk = wave & 1, i = lane & 31, kg = lane >> 5;
;         f32x16_t acc;
; #pragma unroll
;         for (int r = 0; r < 16; ++r) acc[r] = 0.f;
; #pragma unroll
;         for (int s = 0; s < 4; ++s) { const bf16x8_t af = *(const LAS bf16x8_t*)(VT + (32 * eb + i) * GP + 16 * s + 8 * kg), bfr = *(const LAS bf16x8_t*)(KD + (32 * dbk + i) * GP + 16 * s + 8 * kg);
;             acc = __builtin_amdgcn_mfma_f32_32x32x16_bf16(af, bfr, acc, 0, 0, 0); }
;         float* up = UPD + ((size_t)u * 128 + 32 * eb + 4 * kg) * 64 + 32 * dbk + i;
; #pragma unroll
;         for (int r = 0; r < 16; ++r) up[((r & 3) + 8 * (r >> 2)) * 64] = acc[r];
;         GLA_BAR();
;         cur = nxt;
.LBB0_470:
	s_or_b64 exec, exec, s[16:17]
	ds_write_b16 v44, v4 offset:18432
	ds_write_b16_d16_hi v44, v4 offset:18576
	ds_write_b16 v44, v5 offset:18720
	ds_write_b16_d16_hi v44, v5 offset:18864
	ds_write_b16 v44, v6 offset:19008
	ds_write_b16_d16_hi v44, v6 offset:19152
	ds_write_b16 v44, v7 offset:19296
	ds_write_b16_d16_hi v44, v7 offset:19440
	ds_write_b16 v44, v0 offset:27648
	ds_write_b16_d16_hi v44, v0 offset:27792
	ds_write_b16 v44, v1 offset:27936
	ds_write_b16_d16_hi v44, v1 offset:28080
	ds_write_b16 v44, v2 offset:28224
	ds_write_b16_d16_hi v44, v2 offset:28368
	ds_write_b16 v44, v3 offset:28512
	ds_write_b16_d16_hi v44, v3 offset:28656
	s_waitcnt lgkmcnt(0)
	s_barrier
	ds_read_b128 v[0:3], v42 offset:18432
	ds_read_b128 v[4:7], v43
	ds_read_b128 v[36:39], v42 offset:18464
	ds_read_b128 v[46:49], v43 offset:32
	s_movk_i32 s6, 0x1000
	s_waitcnt lgkmcnt(2)
	v_mfma_f32_32x32x16_bf16 v[0:15], v[0:3], v[4:7], 0
	v_add_co_u32_e32 v50, vcc, s6, v40
	v_readlane_b32 s6, v253, 0
	s_nop 0
	v_addc_co_u32_e32 v51, vcc, 0, v41, vcc
	s_add_i32 s31, s31, s6
	v_readlane_b32 s6, v253, 29
	s_waitcnt lgkmcnt(0)
	v_mfma_f32_32x32x16_bf16 v[0:15], v[36:39], v[46:49], v[0:15]
	ds_read_b128 v[36:39], v42 offset:18496
	ds_read_b128 v[46:49], v43 offset:64
	v_readlane_b32 s7, v253, 30
	s_add_i32 s30, s30, s59
	s_and_b64 vcc, exec, s[18:19]
	s_waitcnt lgkmcnt(0)
	v_mfma_f32_32x32x16_bf16 v[0:15], v[36:39], v[46:49], v[0:15]
	ds_read_b128 v[36:39], v42 offset:18528
	ds_read_b128 v[46:49], v43 offset:96
	s_waitcnt lgkmcnt(0)
	v_mfma_f32_32x32x16_bf16 v[0:15], v[36:39], v[46:49], v[0:15]
	s_waitcnt vmcnt(0)
	v_mov_b64_e32 v[38:39], v[22:23]
	v_mov_b64_e32 v[36:37], v[20:21]
	s_nop 9
	global_store_dword v[40:41], v0, off
	global_store_dword v[40:41], v1, off offset:256
	global_store_dword v[40:41], v2, off offset:512
	global_store_dword v[40:41], v3, off offset:768
	global_store_dword v[40:41], v4, off offset:2048
	global_store_dword v[40:41], v5, off offset:2304
	global_store_dword v[40:41], v6, off offset:2560
	global_store_dword v[40:41], v7, off offset:2816
	global_store_dword v[50:51], v8, off
	global_store_dword v[50:51], v9, off offset:256
	global_store_dword v[50:51], v10, off offset:512
	global_store_dword v[50:51], v11, off offset:768
	global_store_dword v[50:51], v12, off offset:2048
	global_store_dword v[50:51], v13, off offset:2304
	global_store_dword v[50:51], v14, off offset:2560
	global_store_dword v[50:51], v15, off offset:2816
	s_waitcnt lgkmcnt(0)
	s_barrier
	v_mov_b64_e32 v[0:1], v[24:25]
	v_mov_b64_e32 v[4:5], v[28:29]
	v_mov_b64_e32 v[8:9], v[32:33]
	v_mov_b64_e32 v[12:13], v[16:17]
	v_lshl_add_u64 v[40:41], v[40:41], 0, s[6:7]
	v_mov_b64_e32 v[2:3], v[26:27]
	v_mov_b64_e32 v[6:7], v[30:31]
	v_mov_b64_e32 v[10:11], v[34:35]
	v_mov_b64_e32 v[14:15], v[18:19]
	s_mov_b32 s6, s34
	s_cbranch_vccnz .LBB0_539

; __device__ __forceinline__ void gla_bcum(const u32x4 a0, const u32x4 a1, const float* wa2, const float* ba, int h, int lane, int wave, float (&bc)[8], float (&bl)[8]) {
;     ...
;     for (int x = 0; x < 8; ++x) { const int col = h * 64 + 8 * wave + x; float z = ba[col];
; #pragma unroll
;         for (int i = 0; i < 16; ++i) z += al[i] * wa2[i * 256 + col];
;         float la = (fminf(z, 0.f) - __logf(1.f + __expf(-fabsf(z)))) * (1.f / 16.f);
;         la += __builtin_bit_cast(float, __builtin_amdgcn_update_dpp(0, __builtin_bit_cast(int, la), 0x111, 0xf, 0xf, true));
;         la += __builtin_bit_cast(float, __builtin_amdgcn_update_dpp(0, __builtin_bit_cast(int, la), 0x112, 0xf, 0xf, true));
;         la += __builtin_bit_cast(float, __builtin_amdgcn_update_dpp(0, __builtin_bit_cast(int, la), 0x114, 0xf, 0xf, true));
;         la += __builtin_bit_cast(float, __builtin_amdgcn_update_dpp(0, __builtin_bit_cast(int, la), 0x118, 0xf, 0xf, true));
;         const float t0 = __builtin_bit_cast(float, __builtin_amdgcn_readlane(__builtin_bit_cast(int, la), 15)), t1 = __builtin_bit_cast(float, __builtin_amdgcn_readlane(__builtin_bit_cast(int, la), 31)),
;                     t2 = __builtin_bit_cast(float, __builtin_amdgcn_readlane(__builtin_bit_cast(int, la), 47)), t3 = __builtin_bit_cast(float, __builtin_amdgcn_readlane(__builtin_bit_cast(int, la), 63));
;         la += (lane >= 48) ? (t0 + t1) + t2 : (lane >= 32) ? t0 + t1 : (lane >= 16) ? t0 : 0.f;
;         bc[x] = la; bl[x] = ((t0 + t1) + t2) + t3; }
.LBB0_527:
	s_andn2_saveexec_b64 s[22:23], s[22:23]
	v_mov_b32_e32 v73, s58
	v_add_f32_e32 v74, s49, v73
	v_add_f32_e32 v73, s47, v74
	s_or_b64 exec, exec, s[22:23]
	s_mov_b32 s6, 0xbfb8aa3b
	s_waitcnt lgkmcnt(0)
	v_mov_b32_e32 v75, s82
	v_fmac_f32_e32 v75, s83, v59
	v_fmac_f32_e32 v75, s84, v58
	v_fmac_f32_e32 v75, s85, v57
	v_fmac_f32_e32 v75, s86, v56
	v_fmac_f32_e32 v75, s87, v55
	v_fmac_f32_e32 v75, s88, v54
	v_fmac_f32_e32 v75, s89, v53
	v_fmac_f32_e32 v75, s90, v52
	v_fmac_f32_e32 v75, s91, v51
	v_fmac_f32_e32 v75, s94, v50
	v_fmac_f32_e32 v75, s95, v49
	v_fmac_f32_e32 v75, s96, v47
	v_fmac_f32_e32 v75, s97, v46
	v_fmac_f32_e32 v75, s51, v38
	v_fmac_f32_e32 v75, s52, v37
	v_fmac_f32_e32 v75, s53, v15
	v_readlane_b32 s82, v255, 29
	v_readlane_b32 s83, v255, 30
	v_readlane_b32 s84, v255, 31
	v_readlane_b32 s85, v255, 32
	v_readlane_b32 s86, v255, 33
	v_readlane_b32 s87, v255, 34
	v_readlane_b32 s88, v255, 35
	v_readlane_b32 s89, v255, 36
	v_readlane_b32 s90, v255, 37
	v_readlane_b32 s91, v255, 38
	v_readlane_b32 s94, v255, 39
	v_readlane_b32 s95, v255, 40
	v_readlane_b32 s96, v255, 41
	v_readlane_b32 s97, v255, 42
	v_readlane_b32 s51, v255, 43
	v_readlane_b32 s52, v255, 44
	v_readlane_b32 s53, v255, 45
	v_mul_f32_e64 v37, |v75|, s6
	v_exp_f32_e32 v37, v37
	s_mov_b32 s6, 0x3f317217
	v_min_f32_e32 v15, 0, v75
	v_add_f32_e32 v37, 1.0, v37
	v_cmp_gt_f32_e32 vcc, s81, v37
	s_nop 1
	v_cndmask_b32_e64 v38, 0, 32, vcc
	v_ldexp_f32 v37, v37, v38
	v_log_f32_e32 v37, v37
	s_nop 0
	v_mul_f32_e32 v38, 0x3f317217, v37
	v_fma_f32 v38, v37, s6, -v38
	v_fmac_f32_e32 v38, 0x3377d1cf, v37
	s_mov_b32 s6, 0x7f800000
	v_fmac_f32_e32 v38, 0x3f317217, v37
	v_cmp_lt_f32_e64 s[16:17], |v37|, s6
	s_nop 1
	v_cndmask_b32_e64 v37, v37, v38, s[16:17]
	v_cndmask_b32_e32 v38, 0, v231, vcc
	v_sub_f32_e32 v37, v37, v38
	v_sub_f32_e32 v15, v15, v37
	v_mul_f32_e32 v37, 0x3d800000, v15
	s_nop 1
	v_mov_b32_dpp v37, v37 row_shr:1 row_mask:0xf bank_mask:0xf bound_ctrl:1
	v_fmac_f32_e32 v37, 0x3d800000, v15
	s_nop 1
	v_add_f32_dpp v15, v37, v37 row_shr:2 row_mask:0xf bank_mask:0xf bound_ctrl:1
	s_nop 1
	v_add_f32_dpp v15, v15, v15 row_shr:4 row_mask:0xf bank_mask:0xf bound_ctrl:1
	s_nop 1
	v_add_f32_dpp v49, v15, v15 row_shr:8 row_mask:0xf bank_mask:0xf bound_ctrl:1
	s_nop 0
	v_readlane_b32 s24, v49, 15
	v_readlane_b32 s25, v49, 31
	v_readlane_b32 s22, v49, 47
	v_readlane_b32 s23, v49, 63
	s_and_saveexec_b64 s[6:7], s[8:9]
	s_xor_b64 s[16:17], exec, s[6:7]
	s_cbranch_execz .LBB0_535
	s_and_saveexec_b64 s[6:7], s[10:11]
	s_xor_b64 s[6:7], exec, s[6:7]
	v_mov_b32_e32 v15, s24
	v_cndmask_b32_e64 v50, 0, v15, s[12:13]
	v_mov_b32_e32 v15, s25
	v_add_f32_e32 v51, s24, v15
	s_andn2_saveexec_b64 s[20:21], s[6:7]
	v_mov_b32_e32 v15, s25
	v_add_f32_e32 v50, s24, v15
	v_mov_b32_e32 v51, v50
	s_or_b64 exec, exec, s[20:21]
